# mLSTM chunk loop: gate prefix-max scan by DPP row shifts/broadcasts instead of six ds_bpermute round trips (on top of full-line GEMM staging)
# speedup vs baseline: 1.0047x; 1.0047x over previous
.LBB0_671:
	s_andn2_b64 vcc, exec, s[74:75]
	s_cbranch_vccnz .LBB0_675
	ds_read_b64 v[2:3], v156
	v_max_f32_e32 v4, v171, v171
	s_waitcnt lgkmcnt(0)
	v_max_f32_e32 v1, v3, v3
	s_nop 1
	v_max_f32_dpp v1, v1, v1 row_shr:1 row_mask:0xf bank_mask:0xf
	s_nop 1
	v_max_f32_dpp v1, v1, v1 row_shr:2 row_mask:0xf bank_mask:0xf
	s_nop 1
	v_max_f32_dpp v1, v1, v1 row_shr:4 row_mask:0xf bank_mask:0xf
	s_nop 1
	v_max_f32_dpp v1, v1, v1 row_shr:8 row_mask:0xf bank_mask:0xf
	s_nop 1
	v_max_f32_dpp v1, v1, v1 row_bcast:15 row_mask:0xa bank_mask:0xf
	s_nop 1
	v_max_f32_dpp v1, v1, v1 row_bcast:31 row_mask:0xc bank_mask:0xf
	s_nop 1
	ds_bpermute_b32 v3, v130, v1
	ds_bpermute_b32 v0, v130, v2
	v_max_f32_e32 v1, v1, v1
	v_max_f32_e32 v1, v4, v1
	v_add_f32_e32 v1, v2, v1
	s_waitcnt lgkmcnt(1)
	v_max_f32_e32 v3, v3, v3
	v_sub_f32_e32 v2, v2, v1
	v_max_f32_e32 v3, v4, v3
	s_waitcnt lgkmcnt(0)
	v_add_f32_e32 v172, v3, v0
	v_mul_f32_e32 v3, 0x3fb8aa3b, v2
	v_add_f32_e32 v2, v171, v2
	v_mul_f32_e32 v2, 0x3fb8aa3b, v2
	v_mul_f32_e32 v1, 0xbfb8aa3b, v1
	v_exp_f32_e32 v3, v3
	v_exp_f32_e32 v2, v2
	v_exp_f32_e32 v1, v1
	ds_write2st64_b32 v137, v3, v2 offset1:1
	ds_write_b32 v137, v1 offset:512
	s_and_saveexec_b64 s[4:5], s[10:11]
	s_cbranch_execz .LBB0_674
	v_sub_f32_e32 v1, v0, v172
	v_add_f32_e32 v0, v171, v0
	v_sub_f32_e32 v0, v0, v172
	v_mul_f32_e32 v1, 0x3fb8aa3b, v1
	v_mul_f32_e32 v0, 0x3fb8aa3b, v0
	v_exp_f32_e32 v1, v1
	v_exp_f32_e32 v0, v0
	v_mov_b32_e32 v2, s3
	ds_write_b64 v2, v[0:1]
